# v1 plus 4-byte pads so the P1a and P1b K-loop heads are also at 4 mod 8 like P8
# baseline (speedup 1.0000x reference)
; #define LAS __attribute__((address_space(3)))
; __device__ __forceinline__ unsigned xb_add(unsigned* p, unsigned v) { return __hip_atomic_fetch_add(p, v, __ATOMIC_RELAXED, __HIP_MEMORY_SCOPE_AGENT); }
; __device__ __forceinline__ unsigned xb_xcc_id() { return (unsigned)__builtin_amdgcn_s_getreg((3 << 11) | 20) & 0xFu; }
; __device__ __forceinline__ KArgs kargs_now() { KArgs p = (KArgs)__builtin_amdgcn_kernarg_segment_ptr(); asm volatile("" : "+s"(p)); return p; }
; __device__ __forceinline__ XcdBarrier xcd_barrier_post(unsigned* bar, volatile LAS unsigned* st) {
;     XcdBarrier b; b.bar = bar; b.x = xb_xcc_id(); b.st = st;
;     if (threadIdx.x == 0) (void)xb_add(&bar[XB_XCNT(b.x)], 1u);
;     return b;
; }
; __global__ void __launch_bounds__(NTHR, 2) fwd_megakernel(Args args_unused) {
;     ...
;     grid.sync();
;     XcdBarrier xbar;
;     { const KArgs A0 = kargs_now(); xbar = xcd_barrier_post((unsigned*)A0->ws, xst); }
.LBB0_102:
	s_or_b64 exec, exec, s[4:5]
	s_mov_b64 s[0:1], s[28:29]
	s_barrier
	s_nop 0
	s_load_dwordx2 s[44:45], s[0:1], 0xe0
	s_getreg_b32 s0, hwreg(HW_REG_XCC_ID, 0, 4)
	s_and_b32 s0, s0, 15
	v_cmp_eq_u32_e64 s[6:7], 0, v230
	s_mov_b64 s[4:5], exec
	s_nop 0
	v_writelane_b32 v254, s6, 5
	s_nop 1
	v_writelane_b32 v254, s7, 6
	s_and_b64 s[6:7], s[4:5], s[6:7]
	s_mov_b64 exec, s[6:7]
	s_cbranch_execz .LBB0_105
	s_mov_b64 s[6:7], exec
	v_mbcnt_lo_u32_b32 v0, s6, 0
	v_mbcnt_hi_u32_b32 v0, s7, v0
	v_cmp_eq_u32_e32 vcc, 0, v0
	s_and_b64 s[8:9], exec, vcc
	s_mov_b64 exec, s[8:9]
	s_cbranch_execz .LBB0_105
	s_lshl_b32 s1, s0, 8
	s_bcnt1_i32_b64 s3, s[6:7]
	v_mov_b32_e32 v0, s1
	v_mov_b32_e32 v1, s3
	s_waitcnt lgkmcnt(0)
	global_atomic_add v0, v1, s[44:45] offset:1024

; #define PG8_WAIT_V(n) asm volatile("s_waitcnt vmcnt(" #n ")" ::: "memory")
; #define PG8_BAR __builtin_amdgcn_s_barrier()
; __device__ __forceinline__ unsigned xb_add(unsigned* p, unsigned v) { return __hip_atomic_fetch_add(p, v, __ATOMIC_RELAXED, __HIP_MEMORY_SCOPE_AGENT); }
; template <class Epi, class Sched, bool ALIGN_EPI = false, bool SP2 = false, bool FP8 = false, bool MIX8 = false>
; __device__ __forceinline__ void gemm_phase(PG8_LAS unsigned char* lds, const Gemm g, const Sched& S, const Epi& E) {
;     ...
;     PG8_WAIT_V(0);
;     if constexpr (!ALIGN_EPI) { if (wr == 0) PG8_BAR; }
;     PG8_BAR;
; __device__ __forceinline__ void xcd_barrier(const XcdBarrier& b) {
;     asm volatile("s_waitcnt vmcnt(0)" ::: "memory");
;     __syncthreads();
;     if (threadIdx.x == 0) {
;         unsigned* bar = b.bar;
;         __builtin_amdgcn_s_waitcnt(0);
;         unsigned nloc = b.st[0], nx = b.st[1];
;         if (nloc == 0u) { xcd_barrier_complete(bar, b.x, nloc, nx); b.st[0] = nloc; b.st[1] = nx; }
;         const unsigned old = xb_add(&bar[XB_XSUB(b.x)], 1u);
.LBB0_203:
	s_waitcnt vmcnt(0)
	s_waitcnt vmcnt(0) lgkmcnt(0)
	s_barrier
	s_nop 0
	s_mov_b64 s[4:5], exec
	v_readlane_b32 s6, v254, 5
	v_readlane_b32 s7, v254, 6
	s_and_b64 s[6:7], s[4:5], s[6:7]
	s_mov_b64 exec, s[6:7]
	s_cbranch_execz .LBB0_255
	s_add_i32 s1, 0, 0x20000
	v_mov_b32_e32 v0, s1
	s_waitcnt vmcnt(0) expcnt(0) lgkmcnt(0)
	ds_read_b32 v2, v0
	s_add_i32 s1, 0, 0x20004
	v_mov_b32_e32 v0, s1
	ds_read_b32 v0, v0
	s_waitcnt lgkmcnt(1)
	v_cmp_ne_u32_e32 vcc, 0, v2
	s_cbranch_vccnz .LBB0_219
	s_add_u32 s6, s44, 0x1000
	s_addc_u32 s7, s45, 0
	s_add_u32 s8, s44, 0x1100
	s_addc_u32 s9, s45, 0
	s_add_u32 s10, s44, 0x1200
	v_readlane_b32 s1, v254, 0
	s_addc_u32 s11, s45, 0
	s_mul_i32 s1, s41, s1
	s_add_u32 s12, s44, 0x1300
	s_mul_i32 s1, s1, s40
	s_addc_u32 s13, s45, 0
	s_mov_b32 s3, 1
	v_mov_b32_e32 v16, 0
	s_branch .LBB0_207
